# sample-unit compressed branch: bf16 row loads 4 in flight instead of serialized; NSA_QB table rebalanced to 234/274
# baseline (speedup 1.0000x reference)
_ZL6NSA_QB:
	.byte	109, 56, 41, 28, 118, 97, 15, 5, 98, 67, 42, 27, 95, 91, 45, 3, 103, 58, 48, 25, 112, 69, 34, 18, 83, 78, 71, 1, 70, 68, 55, 40, 86, 77, 38, 33, 111, 79, 23, 20, 116, 102, 9, 7, 120, 96, 12, 6, 119, 59, 32, 24, 113, 80, 37, 4, 108, 87, 30, 10, 92, 61, 52, 29, 115, 89, 62, 8, 127, 110, 35, 2, 99, 93, 60, 22, 122, 114, 21, 17, 117, 104, 39, 14, 123, 101, 50, 0, 106, 88, 44, 36, 126, 72, 57, 19, 121, 94, 43, 16, 85, 76, 66, 47, 105, 84, 74, 11, 82, 81, 65, 46, 100, 90, 54, 31, 107, 63, 53, 51, 125, 73, 64, 13, 124, 75, 49, 26
	.size	_ZL6NSA_QB, 128

	.type	__hip_cuid_aaa9f4bcd633d1df,@object
